# MIX3: odd workgroups run the HGRN pass-3 item before the RG-LRU final pass so the two halves' bandwidth bursts do not coincide
# speedup vs baseline: 1.0063x; 1.0014x over previous
.LBB0_288:
	s_and_b64 vcc, exec, s[2:3]
	s_cbranch_vccz .LBB0_361
	s_mov_b32 s15, 0
	v_writelane_b32 v255, s15, 30
	v_readlane_b32 s2, v251, 38
	v_readlane_b32 s3, v251, 39
	s_andn2_b64 vcc, exec, s[2:3]
	v_readlane_b32 s2, v253, 47
	v_readlane_b32 s22, v253, 45
	v_readlane_b32 s34, v253, 41
	v_readlane_b32 s12, v254, 3
	v_readlane_b32 s3, v253, 48
	v_readlane_b32 s23, v253, 46
	v_readlane_b32 s35, v253, 42
	s_mov_b32 s14, s12
	v_readlane_b32 s13, v254, 4
	s_cbranch_vccnz .LBB0_357
	v_readlane_b32 s15, v251, 8
	s_cmp_eq_u32 s15, 0
	s_cbranch_scc1 .LBB0_290
	s_bitcmp1_b32 s12, 0
	s_cbranch_scc0 .LBB0_290
	s_mov_b32 s15, 1
	v_writelane_b32 v255, s15, 30
	s_branch .Lm3_hgrn_setup
.LBB0_290:
	s_waitcnt vmcnt(0)
	v_mov_b32_e32 v2, v178
	s_add_u32 s20, s2, s10
	v_ashrrev_i32_e32 v3, 31, v2
	v_lshlrev_b64 v[6:7], 2, v[2:3]
	s_addc_u32 s21, s3, s11
	v_lshl_add_u64 v[4:5], s[20:21], 0, v[6:7]
	s_add_u32 s20, s34, s10
	s_addc_u32 s21, s35, s11
	v_lshl_add_u64 v[6:7], s[20:21], 0, v[6:7]
	s_mov_b32 s15, 0x3df00000
	global_load_dword v65, v[6:7], off
	v_add_co_u32_e32 v6, vcc, s15, v4
	s_mov_b32 s15, 0x3df01000
	s_nop 0
	v_addc_co_u32_e32 v7, vcc, 0, v5, vcc
	v_add_co_u32_e32 v8, vcc, s15, v4
	s_mov_b32 s15, 0x3df02000
	s_nop 0
	v_addc_co_u32_e32 v9, vcc, 0, v5, vcc
	global_load_dword v67, v[8:9], off offset:-4096
	global_load_dword v66, v[6:7], off offset:2048
	global_load_dword v64, v[8:9], off
	global_load_dword v61, v[8:9], off offset:2048
	v_add_co_u32_e32 v6, vcc, s15, v4
	s_mov_b32 s15, 0x3df03000
	s_nop 0
	v_addc_co_u32_e32 v7, vcc, 0, v5, vcc
	v_add_co_u32_e32 v8, vcc, s15, v4
	s_mov_b32 s15, 0x3df04000
	s_nop 0
	v_addc_co_u32_e32 v9, vcc, 0, v5, vcc
	global_load_dword v63, v[8:9], off offset:-4096
	global_load_dword v60, v[6:7], off offset:2048
	global_load_dword v58, v[8:9], off
	global_load_dword v56, v[8:9], off offset:2048
	v_add_co_u32_e32 v6, vcc, s15, v4
	s_mov_b32 s15, 0x3df05000
	s_nop 0
	v_addc_co_u32_e32 v7, vcc, 0, v5, vcc
	v_add_co_u32_e32 v8, vcc, s15, v4
	s_mov_b32 s15, 0x3df06000
	s_nop 0
	v_addc_co_u32_e32 v9, vcc, 0, v5, vcc
	global_load_dword v62, v[8:9], off offset:-4096
	global_load_dword v59, v[6:7], off offset:2048
	global_load_dword v57, v[8:9], off
	global_load_dword v54, v[8:9], off offset:2048
	v_add_co_u32_e32 v6, vcc, s15, v4
	s_mov_b32 s15, 0x3df07000
	s_nop 0
	v_addc_co_u32_e32 v7, vcc, 0, v5, vcc
	v_add_co_u32_e32 v8, vcc, s15, v4
	s_mov_b32 s15, 0x3df08000
	s_nop 0
	v_addc_co_u32_e32 v9, vcc, 0, v5, vcc
	global_load_dword v55, v[8:9], off offset:-4096
	global_load_dword v53, v[6:7], off offset:2048
	global_load_dword v52, v[8:9], off
	global_load_dword v49, v[8:9], off offset:2048
	v_add_co_u32_e32 v6, vcc, s15, v4
	s_mov_b32 s15, 0x3df09000
	s_nop 0
	v_addc_co_u32_e32 v7, vcc, 0, v5, vcc
	v_add_co_u32_e32 v8, vcc, s15, v4
	s_mov_b32 s15, 0x3df0a000
	s_nop 0
	v_addc_co_u32_e32 v9, vcc, 0, v5, vcc
	global_load_dword v51, v[8:9], off offset:-4096
	global_load_dword v48, v[6:7], off offset:2048
	global_load_dword v46, v[8:9], off
	global_load_dword v44, v[8:9], off offset:2048
	v_add_co_u32_e32 v6, vcc, s15, v4
	s_mov_b32 s15, 0x3df0b000
	s_nop 0
	v_addc_co_u32_e32 v7, vcc, 0, v5, vcc
	v_add_co_u32_e32 v8, vcc, s15, v4
	s_mov_b32 s15, 0x3df0c000
	s_nop 0
	v_addc_co_u32_e32 v9, vcc, 0, v5, vcc
	global_load_dword v50, v[8:9], off offset:-4096
	global_load_dword v47, v[6:7], off offset:2048
	global_load_dword v45, v[8:9], off
	global_load_dword v42, v[8:9], off offset:2048
	v_add_co_u32_e32 v6, vcc, s15, v4
	s_mov_b32 s15, 0x3df0d000
	s_nop 0
	v_addc_co_u32_e32 v7, vcc, 0, v5, vcc
	v_add_co_u32_e32 v8, vcc, s15, v4
	s_mov_b32 s15, 0x3df0e000
	s_nop 0
	v_addc_co_u32_e32 v9, vcc, 0, v5, vcc
	global_load_dword v43, v[8:9], off offset:-4096
	global_load_dword v39, v[6:7], off offset:2048
	global_load_dword v37, v[8:9], off
	global_load_dword v34, v[8:9], off offset:2048
	v_add_co_u32_e32 v6, vcc, s15, v4
	s_mov_b32 s15, 0x3df0f000
	s_nop 0
	v_addc_co_u32_e32 v7, vcc, 0, v5, vcc
	v_add_co_u32_e32 v8, vcc, s15, v4
	s_mov_b32 s15, 0x3df10000
	s_nop 0
	v_addc_co_u32_e32 v9, vcc, 0, v5, vcc
	global_load_dword v36, v[8:9], off offset:-4096
	global_load_dword v40, v[6:7], off offset:2048
	global_load_dword v41, v[8:9], off
	global_load_dword v38, v[8:9], off offset:2048
	v_add_co_u32_e32 v6, vcc, s15, v4
	s_mov_b32 s15, 0x3df11000
	s_nop 0
	v_addc_co_u32_e32 v7, vcc, 0, v5, vcc
	v_add_co_u32_e32 v8, vcc, s15, v4
	s_mov_b32 s15, 0x3df12000
	s_nop 0
	v_addc_co_u32_e32 v9, vcc, 0, v5, vcc
	global_load_dword v35, v[8:9], off offset:-4096
	global_load_dword v33, v[6:7], off offset:2048
	global_load_dword v32, v[8:9], off
	global_load_dword v29, v[8:9], off offset:2048
	v_add_co_u32_e32 v6, vcc, s15, v4
	s_mov_b32 s15, 0x3df13000
	s_nop 0
	v_addc_co_u32_e32 v7, vcc, 0, v5, vcc
	v_add_co_u32_e32 v8, vcc, s15, v4
	s_mov_b32 s15, 0x3df14000
	s_nop 0
	v_addc_co_u32_e32 v9, vcc, 0, v5, vcc
	global_load_dword v31, v[8:9], off offset:-4096
	global_load_dword v28, v[6:7], off offset:2048
	global_load_dword v26, v[8:9], off
	global_load_dword v24, v[8:9], off offset:2048
	v_add_co_u32_e32 v6, vcc, s15, v4
	s_mov_b32 s15, 0x3df15000
	s_nop 0
	v_addc_co_u32_e32 v7, vcc, 0, v5, vcc
	v_add_co_u32_e32 v8, vcc, s15, v4
	s_mov_b32 s15, 0x3df16000
	s_nop 0
	v_addc_co_u32_e32 v9, vcc, 0, v5, vcc
	global_load_dword v30, v[8:9], off offset:-4096
	global_load_dword v27, v[6:7], off offset:2048
	global_load_dword v25, v[8:9], off
	global_load_dword v22, v[8:9], off offset:2048
	v_add_co_u32_e32 v6, vcc, s15, v4
	s_mov_b32 s15, 0x3df17000
	s_nop 0
	v_addc_co_u32_e32 v7, vcc, 0, v5, vcc
	v_add_co_u32_e32 v8, vcc, s15, v4
	s_mov_b32 s15, 0x3df18000
	s_nop 0
	v_addc_co_u32_e32 v9, vcc, 0, v5, vcc
	global_load_dword v23, v[8:9], off offset:-4096
	global_load_dword v21, v[6:7], off offset:2048
	global_load_dword v20, v[8:9], off
	global_load_dword v17, v[8:9], off offset:2048
	v_add_co_u32_e32 v6, vcc, s15, v4
	s_mov_b32 s15, 0x3df19000
	s_nop 0
	v_addc_co_u32_e32 v7, vcc, 0, v5, vcc
	v_add_co_u32_e32 v8, vcc, s15, v4
	s_mov_b32 s15, 0x3df1a000
	s_nop 0
	v_addc_co_u32_e32 v9, vcc, 0, v5, vcc
	global_load_dword v19, v[8:9], off offset:-4096
	global_load_dword v16, v[6:7], off offset:2048
	global_load_dword v14, v[8:9], off
	global_load_dword v12, v[8:9], off offset:2048
	v_add_co_u32_e32 v6, vcc, s15, v4
	s_mov_b32 s15, 0x3df1b000
	s_nop 0
	v_addc_co_u32_e32 v7, vcc, 0, v5, vcc
	v_add_co_u32_e32 v8, vcc, s15, v4
	s_mov_b32 s15, 0x3df1c000
	s_nop 0
	v_addc_co_u32_e32 v9, vcc, 0, v5, vcc
	global_load_dword v18, v[8:9], off offset:-4096
	global_load_dword v15, v[6:7], off offset:2048
	global_load_dword v13, v[8:9], off
	global_load_dword v10, v[8:9], off offset:2048
	v_add_co_u32_e32 v6, vcc, s15, v4
	s_mov_b32 s15, 0x3df1d000
	s_nop 0
	v_addc_co_u32_e32 v7, vcc, 0, v5, vcc
	v_add_co_u32_e32 v8, vcc, s15, v4
	s_mov_b32 s15, 0x3df1e000
	s_nop 0
	v_addc_co_u32_e32 v9, vcc, 0, v5, vcc
	global_load_dword v11, v[8:9], off offset:-4096
	s_nop 0
	global_load_dword v7, v[6:7], off offset:2048
	s_nop 0
	global_load_dword v6, v[8:9], off
	global_load_dword v0, v[8:9], off offset:2048
	v_add_co_u32_e32 v8, vcc, s15, v4
	s_mov_b32 s15, 0x3df1f000
	s_nop 0
	v_addc_co_u32_e32 v9, vcc, 0, v5, vcc
	v_add_co_u32_e32 v68, vcc, s15, v4
	s_add_u32 s20, s22, s10
	s_nop 0
	v_addc_co_u32_e32 v69, vcc, 0, v5, vcc
	global_load_dword v4, v[68:69], off offset:-4096
	s_nop 0
	global_load_dword v8, v[8:9], off offset:2048
	s_nop 0
	global_load_dword v9, v[68:69], off
	global_load_dword v5, v[68:69], off offset:2048
	s_addc_u32 s21, s23, s11
	v_lshl_add_u64 v[2:3], v[2:3], 1, s[20:21]
	s_waitcnt vmcnt(62)
	v_lshlrev_b32_e32 v68, 16, v67
	v_mul_f32_e32 v68, 0x3fb8aa3b, v68
	v_exp_f32_e32 v68, v68
	v_lshlrev_b32_e32 v69, 16, v66
	v_and_b32_e32 v67, 0xffff0000, v67
	v_mul_f32_e32 v69, 0x3fb8aa3b, v69
	s_mov_b32 s15, 0x17000000
	v_fmac_f32_e32 v67, v65, v68
	v_exp_f32_e32 v70, v69
	v_add_co_u32_e32 v68, vcc, s15, v2
	v_cvt_pk_bf16_f32 v65, v67, s0
	s_nop 0
	v_addc_co_u32_e32 v69, vcc, 0, v3, vcc
	global_store_short v[68:69], v65, off
	v_and_b32_e32 v65, 0xffff0000, v66
	s_waitcnt vmcnt(62)
	v_lshlrev_b32_e32 v66, 16, v64
	v_mul_f32_e32 v66, 0x3fb8aa3b, v66
	v_fmac_f32_e32 v65, v70, v67
	v_exp_f32_e32 v66, v66
	v_cvt_pk_bf16_f32 v67, v65, s0
	global_store_short v[68:69], v67, off offset:2560
	v_and_b32_e32 v67, 0xffff0000, v64
	s_waitcnt vmcnt(62)
	v_lshlrev_b32_e32 v64, 16, v61
	v_mul_f32_e32 v64, 0x3fb8aa3b, v64
	s_mov_b32 s15, 0x17001000
	v_fmac_f32_e32 v67, v66, v65
	v_exp_f32_e32 v68, v64
	v_add_co_u32_e32 v64, vcc, s15, v2
	v_cvt_pk_bf16_f32 v66, v67, s0
	s_nop 0
	v_addc_co_u32_e32 v65, vcc, 0, v3, vcc
	global_store_short v[64:65], v66, off offset:1024
	s_waitcnt vmcnt(62)
	v_lshlrev_b32_e32 v66, 16, v63
	v_and_b32_e32 v61, 0xffff0000, v61
	v_mul_f32_e32 v66, 0x3fb8aa3b, v66
	v_fmac_f32_e32 v61, v68, v67
	v_exp_f32_e32 v66, v66
	v_cvt_pk_bf16_f32 v67, v61, s0
	global_store_short v[64:65], v67, off offset:3584
	s_waitcnt vmcnt(62)
	v_lshlrev_b32_e32 v64, 16, v60
	v_and_b32_e32 v63, 0xffff0000, v63
	v_mul_f32_e32 v64, 0x3fb8aa3b, v64
	s_mov_b32 s15, 0x17002000
	v_fmac_f32_e32 v63, v66, v61
	v_exp_f32_e32 v66, v64
	v_add_co_u32_e32 v64, vcc, s15, v2
	v_cvt_pk_bf16_f32 v61, v63, s0
	s_nop 0
	v_addc_co_u32_e32 v65, vcc, 0, v3, vcc
	global_store_short v[64:65], v61, off offset:2048
	v_and_b32_e32 v64, 0xffff0000, v60
	s_waitcnt vmcnt(62)
	v_lshlrev_b32_e32 v60, 16, v58
	v_mul_f32_e32 v60, 0x3fb8aa3b, v60
	s_mov_b32 s15, 0x17003000
	v_fmac_f32_e32 v64, v66, v63
	v_exp_f32_e32 v65, v60
	v_add_co_u32_e32 v60, vcc, s15, v2
	v_cvt_pk_bf16_f32 v63, v64, s0
	s_nop 0
	v_addc_co_u32_e32 v61, vcc, 0, v3, vcc
	global_store_short v[60:61], v63, off offset:512
	s_waitcnt vmcnt(62)
	v_lshlrev_b32_e32 v63, 16, v56
	v_and_b32_e32 v58, 0xffff0000, v58
	v_mul_f32_e32 v63, 0x3fb8aa3b, v63
	v_fmac_f32_e32 v58, v65, v64
	v_exp_f32_e32 v63, v63
	v_cvt_pk_bf16_f32 v64, v58, s0
	global_store_short v[60:61], v64, off offset:3072
	s_waitcnt vmcnt(62)
	v_lshlrev_b32_e32 v60, 16, v62
	v_and_b32_e32 v56, 0xffff0000, v56
	v_mul_f32_e32 v60, 0x3fb8aa3b, v60
	s_mov_b32 s15, 0x17004000
	v_fmac_f32_e32 v56, v63, v58
	v_exp_f32_e32 v63, v60
	v_add_co_u32_e32 v60, vcc, s15, v2
	v_cvt_pk_bf16_f32 v58, v56, s0
	s_nop 0
	v_addc_co_u32_e32 v61, vcc, 0, v3, vcc
	global_store_short v[60:61], v58, off offset:1536
	s_waitcnt vmcnt(62)
	v_lshlrev_b32_e32 v60, 16, v59
	v_mul_f32_e32 v60, 0x3fb8aa3b, v60
	v_and_b32_e32 v58, 0xffff0000, v62
	v_exp_f32_e32 v62, v60
	s_mov_b32 s15, 0x17005000
	v_fmac_f32_e32 v58, v63, v56
	v_add_co_u32_e32 v60, vcc, s15, v2
	v_cvt_pk_bf16_f32 v56, v58, s0
	s_nop 0
	v_addc_co_u32_e32 v61, vcc, 0, v3, vcc
	global_store_short v[60:61], v56, off
	v_and_b32_e32 v56, 0xffff0000, v59
	v_fmac_f32_e32 v56, v62, v58
	s_waitcnt vmcnt(62)
	v_lshlrev_b32_e32 v58, 16, v57
	v_mul_f32_e32 v58, 0x3fb8aa3b, v58
	v_exp_f32_e32 v58, v58
	v_cvt_pk_bf16_f32 v59, v56, s0
	global_store_short v[60:61], v59, off offset:2560
	v_and_b32_e32 v59, 0xffff0000, v57
	v_fmac_f32_e32 v59, v58, v56
	s_waitcnt vmcnt(62)
	v_lshlrev_b32_e32 v56, 16, v54
	v_mul_f32_e32 v56, 0x3fb8aa3b, v56
	s_mov_b32 s15, 0x17006000
	v_exp_f32_e32 v60, v56
	v_add_co_u32_e32 v56, vcc, s15, v2
	v_cvt_pk_bf16_f32 v58, v59, s0
	s_nop 0
	v_addc_co_u32_e32 v57, vcc, 0, v3, vcc
	global_store_short v[56:57], v58, off offset:1024
	s_waitcnt vmcnt(62)
	v_lshlrev_b32_e32 v58, 16, v55
	v_mul_f32_e32 v58, 0x3fb8aa3b, v58
	v_and_b32_e32 v54, 0xffff0000, v54
	v_exp_f32_e32 v58, v58
	v_fmac_f32_e32 v54, v60, v59
	v_cvt_pk_bf16_f32 v59, v54, s0
	global_store_short v[56:57], v59, off offset:3584
	v_and_b32_e32 v56, 0xffff0000, v55
	v_fmac_f32_e32 v56, v58, v54
	s_waitcnt vmcnt(62)
	v_lshlrev_b32_e32 v54, 16, v53
	v_mul_f32_e32 v54, 0x3fb8aa3b, v54
	s_mov_b32 s15, 0x17007000
	v_exp_f32_e32 v58, v54
	v_add_co_u32_e32 v54, vcc, s15, v2
	v_cvt_pk_bf16_f32 v57, v56, s0
	s_nop 0
	v_addc_co_u32_e32 v55, vcc, 0, v3, vcc
	global_store_short v[54:55], v57, off offset:2048
	s_waitcnt vmcnt(62)
	v_lshlrev_b32_e32 v54, 16, v52
	v_mul_f32_e32 v54, 0x3fb8aa3b, v54
	v_exp_f32_e32 v57, v54
	v_and_b32_e32 v53, 0xffff0000, v53
	v_fmac_f32_e32 v53, v58, v56
	v_and_b32_e32 v52, 0xffff0000, v52
	v_cvt_pk_bf16_f32 v56, v53, s0
	v_fmac_f32_e32 v52, v57, v53
	s_waitcnt vmcnt(61)
	v_lshlrev_b32_e32 v53, 16, v49
	v_mul_f32_e32 v53, 0x3fb8aa3b, v53
	v_exp_f32_e32 v53, v53
	s_mov_b32 s15, 0x17008000
	v_add_co_u32_e32 v54, vcc, s15, v2
	v_and_b32_e32 v49, 0xffff0000, v49
	s_nop 0
	v_addc_co_u32_e32 v55, vcc, 0, v3, vcc
	global_store_short v[54:55], v56, off offset:512
	v_cvt_pk_bf16_f32 v56, v52, s0
	v_fmac_f32_e32 v49, v53, v52
	s_waitcnt vmcnt(61)
	v_lshlrev_b32_e32 v52, 16, v51
	v_mul_f32_e32 v52, 0x3fb8aa3b, v52
	s_mov_b32 s15, 0x17009000
	global_store_short v[54:55], v56, off offset:3072
	v_exp_f32_e32 v55, v52
	v_add_co_u32_e32 v52, vcc, s15, v2
	v_cvt_pk_bf16_f32 v54, v49, s0
	s_nop 0
	v_addc_co_u32_e32 v53, vcc, 0, v3, vcc
	global_store_short v[52:53], v54, off offset:1536
	s_waitcnt vmcnt(62)
	v_lshlrev_b32_e32 v52, 16, v48
	v_and_b32_e32 v51, 0xffff0000, v51
	v_mul_f32_e32 v52, 0x3fb8aa3b, v52
	s_mov_b32 s15, 0x1700a000
	v_fmac_f32_e32 v51, v55, v49
	v_exp_f32_e32 v54, v52
	v_add_co_u32_e32 v52, vcc, s15, v2
	v_cvt_pk_bf16_f32 v49, v51, s0
	s_nop 0
	v_addc_co_u32_e32 v53, vcc, 0, v3, vcc
	global_store_short v[52:53], v49, off
	s_waitcnt vmcnt(62)
	v_lshlrev_b32_e32 v49, 16, v46
	v_mul_f32_e32 v49, 0x3fb8aa3b, v49
	v_exp_f32_e32 v49, v49
	v_and_b32_e32 v48, 0xffff0000, v48
	v_fmac_f32_e32 v48, v54, v51
	v_and_b32_e32 v46, 0xffff0000, v46
	v_cvt_pk_bf16_f32 v51, v48, s0
	v_fmac_f32_e32 v46, v49, v48
	s_waitcnt vmcnt(61)
	v_lshlrev_b32_e32 v48, 16, v44
	v_mul_f32_e32 v48, 0x3fb8aa3b, v48
	global_store_short v[52:53], v51, off offset:2560
	v_exp_f32_e32 v52, v48
	v_and_b32_e32 v44, 0xffff0000, v44
	v_cvt_pk_bf16_f32 v51, v46, s0
	s_mov_b32 s15, 0x1700b000
	v_fmac_f32_e32 v44, v52, v46
	s_waitcnt vmcnt(61)
	v_lshlrev_b32_e32 v46, 16, v50
	v_mul_f32_e32 v46, 0x3fb8aa3b, v46
	v_exp_f32_e32 v46, v46
	v_and_b32_e32 v50, 0xffff0000, v50
	v_add_co_u32_e32 v48, vcc, s15, v2
	v_fmac_f32_e32 v50, v46, v44
	s_waitcnt vmcnt(60)
	v_lshlrev_b32_e32 v46, 16, v47
	v_addc_co_u32_e32 v49, vcc, 0, v3, vcc
	v_mul_f32_e32 v46, 0x3fb8aa3b, v46
	global_store_short v[48:49], v51, off offset:1024
	v_cvt_pk_bf16_f32 v51, v44, s0
	v_exp_f32_e32 v46, v46
	s_mov_b32 s15, 0x1700c000
	global_store_short v[48:49], v51, off offset:3584
	v_add_co_u32_e32 v48, vcc, s15, v2
	v_cvt_pk_bf16_f32 v44, v50, s0
	s_nop 0
	v_addc_co_u32_e32 v49, vcc, 0, v3, vcc
	global_store_short v[48:49], v44, off offset:2048
	v_and_b32_e32 v44, 0xffff0000, v47
	v_fmac_f32_e32 v44, v46, v50
	s_waitcnt vmcnt(62)
	v_lshlrev_b32_e32 v46, 16, v45
	v_mul_f32_e32 v46, 0x3fb8aa3b, v46
	v_exp_f32_e32 v49, v46
	v_and_b32_e32 v45, 0xffff0000, v45
	v_cvt_pk_bf16_f32 v48, v44, s0
	s_mov_b32 s15, 0x1700d000
	v_fmac_f32_e32 v45, v49, v44
	s_waitcnt vmcnt(61)
	v_lshlrev_b32_e32 v44, 16, v42
	v_mul_f32_e32 v44, 0x3fb8aa3b, v44
	v_exp_f32_e32 v44, v44
	v_add_co_u32_e32 v46, vcc, s15, v2
	v_and_b32_e32 v42, 0xffff0000, v42
	s_nop 0
	v_addc_co_u32_e32 v47, vcc, 0, v3, vcc
	v_fmac_f32_e32 v42, v44, v45
	s_waitcnt vmcnt(60)
	v_lshlrev_b32_e32 v44, 16, v43
	global_store_short v[46:47], v48, off offset:512
	v_cvt_pk_bf16_f32 v48, v45, s0
	v_mul_f32_e32 v44, 0x3fb8aa3b, v44
	global_store_short v[46:47], v48, off offset:3072
	v_exp_f32_e32 v47, v44
	s_mov_b32 s15, 0x1700e000
	v_add_co_u32_e32 v44, vcc, s15, v2
	v_cvt_pk_bf16_f32 v46, v42, s0
	s_nop 0
	v_addc_co_u32_e32 v45, vcc, 0, v3, vcc
	global_store_short v[44:45], v46, off offset:1536
	v_and_b32_e32 v44, 0xffff0000, v43
	v_fmac_f32_e32 v44, v47, v42
	s_waitcnt vmcnt(62)
	v_lshlrev_b32_e32 v42, 16, v39
	v_mul_f32_e32 v42, 0x3fb8aa3b, v42
	v_exp_f32_e32 v46, v42
	v_and_b32_e32 v39, 0xffff0000, v39
	v_cvt_pk_bf16_f32 v45, v44, s0
	s_mov_b32 s15, 0x1700f000
	v_fmac_f32_e32 v39, v46, v44
	s_waitcnt vmcnt(61)
	v_lshlrev_b32_e32 v44, 16, v37
	v_add_co_u32_e32 v42, vcc, s15, v2
	v_mul_f32_e32 v44, 0x3fb8aa3b, v44
	s_nop 0
	v_addc_co_u32_e32 v43, vcc, 0, v3, vcc
	v_exp_f32_e32 v44, v44
	global_store_short v[42:43], v45, off
	v_cvt_pk_bf16_f32 v45, v39, s0
	global_store_short v[42:43], v45, off offset:2560
	s_waitcnt vmcnt(62)
	v_lshlrev_b32_e32 v42, 16, v34
	v_and_b32_e32 v37, 0xffff0000, v37
	v_mul_f32_e32 v42, 0x3fb8aa3b, v42
	v_fmac_f32_e32 v37, v44, v39
	v_exp_f32_e32 v44, v42
	v_and_b32_e32 v34, 0xffff0000, v34
	v_cvt_pk_bf16_f32 v39, v37, s0
	s_mov_b32 s15, 0x17010000
	v_fmac_f32_e32 v34, v44, v37
	s_waitcnt vmcnt(61)
	v_lshlrev_b32_e32 v37, 16, v36
	v_add_co_u32_e32 v42, vcc, s15, v2
	v_mul_f32_e32 v37, 0x3fb8aa3b, v37
	s_nop 0
	v_addc_co_u32_e32 v43, vcc, 0, v3, vcc
	v_exp_f32_e32 v37, v37
	global_store_short v[42:43], v39, off offset:1024
	v_cvt_pk_bf16_f32 v39, v34, s0
	global_store_short v[42:43], v39, off offset:3584
	v_and_b32_e32 v39, 0xffff0000, v36
	s_waitcnt vmcnt(62)
	v_lshlrev_b32_e32 v36, 16, v40
	v_mul_f32_e32 v36, 0x3fb8aa3b, v36
	s_mov_b32 s15, 0x17011000
	v_fmac_f32_e32 v39, v37, v34
	v_exp_f32_e32 v42, v36
	v_add_co_u32_e32 v36, vcc, s15, v2
	v_cvt_pk_bf16_f32 v34, v39, s0
	s_nop 0
	v_addc_co_u32_e32 v37, vcc, 0, v3, vcc
	global_store_short v[36:37], v34, off offset:2048
	s_waitcnt vmcnt(62)
	v_lshlrev_b32_e32 v36, 16, v41
	v_mul_f32_e32 v36, 0x3fb8aa3b, v36
	v_and_b32_e32 v34, 0xffff0000, v40
	v_exp_f32_e32 v40, v36
	s_mov_b32 s15, 0x17012000
	v_fmac_f32_e32 v34, v42, v39
	v_add_co_u32_e32 v36, vcc, s15, v2
	v_cvt_pk_bf16_f32 v39, v34, s0
	s_nop 0
	v_addc_co_u32_e32 v37, vcc, 0, v3, vcc
	global_store_short v[36:37], v39, off offset:512
	v_and_b32_e32 v39, 0xffff0000, v41
	v_fmac_f32_e32 v39, v40, v34
	s_waitcnt vmcnt(62)
	v_lshlrev_b32_e32 v34, 16, v38
	v_mul_f32_e32 v34, 0x3fb8aa3b, v34
	v_exp_f32_e32 v34, v34
	v_cvt_pk_bf16_f32 v40, v39, s0
	global_store_short v[36:37], v40, off offset:3072
	s_waitcnt vmcnt(62)
	v_lshlrev_b32_e32 v36, 16, v35
	v_and_b32_e32 v38, 0xffff0000, v38
	v_mul_f32_e32 v36, 0x3fb8aa3b, v36
	s_mov_b32 s15, 0x17013000
	v_fmac_f32_e32 v38, v34, v39
	v_exp_f32_e32 v39, v36
	v_add_co_u32_e32 v36, vcc, s15, v2
	v_cvt_pk_bf16_f32 v34, v38, s0
	s_nop 0
	v_addc_co_u32_e32 v37, vcc, 0, v3, vcc
	global_store_short v[36:37], v34, off offset:1536
	s_waitcnt vmcnt(62)
	v_lshlrev_b32_e32 v34, 16, v33
	v_and_b32_e32 v36, 0xffff0000, v35
	v_mul_f32_e32 v34, 0x3fb8aa3b, v34
	v_fmac_f32_e32 v36, v39, v38
	v_exp_f32_e32 v38, v34
	v_and_b32_e32 v33, 0xffff0000, v33
	v_cvt_pk_bf16_f32 v37, v36, s0
	s_mov_b32 s15, 0x17014000
	v_fmac_f32_e32 v33, v38, v36
	s_waitcnt vmcnt(61)
	v_lshlrev_b32_e32 v36, 16, v32
	v_add_co_u32_e32 v34, vcc, s15, v2
	v_mul_f32_e32 v36, 0x3fb8aa3b, v36
	s_nop 0
	v_addc_co_u32_e32 v35, vcc, 0, v3, vcc
	v_exp_f32_e32 v36, v36
	global_store_short v[34:35], v37, off
	v_cvt_pk_bf16_f32 v37, v33, s0
	global_store_short v[34:35], v37, off offset:2560
	v_and_b32_e32 v34, 0xffff0000, v32
	s_waitcnt vmcnt(62)
	v_lshlrev_b32_e32 v32, 16, v29
	v_mul_f32_e32 v32, 0x3fb8aa3b, v32
	v_fmac_f32_e32 v34, v36, v33
	v_exp_f32_e32 v36, v32
	v_and_b32_e32 v29, 0xffff0000, v29
	v_cvt_pk_bf16_f32 v35, v34, s0
	s_mov_b32 s15, 0x17015000
	v_fmac_f32_e32 v29, v36, v34
	s_waitcnt vmcnt(61)
	v_lshlrev_b32_e32 v34, 16, v31
	v_add_co_u32_e32 v32, vcc, s15, v2
	v_mul_f32_e32 v34, 0x3fb8aa3b, v34
	s_nop 0
	v_addc_co_u32_e32 v33, vcc, 0, v3, vcc
	v_exp_f32_e32 v34, v34
	global_store_short v[32:33], v35, off offset:1024
	v_cvt_pk_bf16_f32 v35, v29, s0
	global_store_short v[32:33], v35, off offset:3584
	s_waitcnt vmcnt(62)
	v_lshlrev_b32_e32 v32, 16, v28
	v_and_b32_e32 v31, 0xffff0000, v31
	v_mul_f32_e32 v32, 0x3fb8aa3b, v32
	s_mov_b32 s15, 0x17016000
	v_fmac_f32_e32 v31, v34, v29
	v_exp_f32_e32 v34, v32
	v_add_co_u32_e32 v32, vcc, s15, v2
	v_cvt_pk_bf16_f32 v29, v31, s0
	s_nop 0
	v_addc_co_u32_e32 v33, vcc, 0, v3, vcc
	global_store_short v[32:33], v29, off offset:2048
	v_and_b32_e32 v32, 0xffff0000, v28
	s_waitcnt vmcnt(62)
	v_lshlrev_b32_e32 v28, 16, v26
	v_mul_f32_e32 v28, 0x3fb8aa3b, v28
	s_mov_b32 s15, 0x17017000
	v_fmac_f32_e32 v32, v34, v31
	v_exp_f32_e32 v33, v28
	v_add_co_u32_e32 v28, vcc, s15, v2
	v_cvt_pk_bf16_f32 v31, v32, s0
	s_nop 0
	v_addc_co_u32_e32 v29, vcc, 0, v3, vcc
	global_store_short v[28:29], v31, off offset:512
	s_waitcnt vmcnt(62)
	v_lshlrev_b32_e32 v31, 16, v24
	v_and_b32_e32 v26, 0xffff0000, v26
	v_mul_f32_e32 v31, 0x3fb8aa3b, v31
	v_fmac_f32_e32 v26, v33, v32
	v_exp_f32_e32 v31, v31
	v_cvt_pk_bf16_f32 v32, v26, s0
	global_store_short v[28:29], v32, off offset:3072
	s_waitcnt vmcnt(62)
	v_lshlrev_b32_e32 v28, 16, v30
	v_and_b32_e32 v24, 0xffff0000, v24
	v_mul_f32_e32 v28, 0x3fb8aa3b, v28
	s_mov_b32 s15, 0x17018000
	v_fmac_f32_e32 v24, v31, v26
	v_exp_f32_e32 v31, v28
	v_add_co_u32_e32 v28, vcc, s15, v2
	v_cvt_pk_bf16_f32 v26, v24, s0
	s_nop 0
	v_addc_co_u32_e32 v29, vcc, 0, v3, vcc
	global_store_short v[28:29], v26, off offset:1536
	s_waitcnt vmcnt(62)
	v_lshlrev_b32_e32 v28, 16, v27
	v_mul_f32_e32 v28, 0x3fb8aa3b, v28
	v_and_b32_e32 v26, 0xffff0000, v30
	v_exp_f32_e32 v30, v28
	s_mov_b32 s15, 0x17019000
	v_fmac_f32_e32 v26, v31, v24
	v_add_co_u32_e32 v28, vcc, s15, v2
	v_cvt_pk_bf16_f32 v24, v26, s0
	s_nop 0
	v_addc_co_u32_e32 v29, vcc, 0, v3, vcc
	global_store_short v[28:29], v24, off
	v_and_b32_e32 v24, 0xffff0000, v27
	v_fmac_f32_e32 v24, v30, v26
	s_waitcnt vmcnt(62)
	v_lshlrev_b32_e32 v26, 16, v25
	v_mul_f32_e32 v26, 0x3fb8aa3b, v26
	v_exp_f32_e32 v26, v26
	v_cvt_pk_bf16_f32 v27, v24, s0
	global_store_short v[28:29], v27, off offset:2560
	v_and_b32_e32 v27, 0xffff0000, v25
	v_fmac_f32_e32 v27, v26, v24
	s_waitcnt vmcnt(62)
	v_lshlrev_b32_e32 v24, 16, v22
	v_mul_f32_e32 v24, 0x3fb8aa3b, v24
	s_mov_b32 s15, 0x1701a000
	v_exp_f32_e32 v28, v24
	v_add_co_u32_e32 v24, vcc, s15, v2
	v_cvt_pk_bf16_f32 v26, v27, s0
	s_nop 0
	v_addc_co_u32_e32 v25, vcc, 0, v3, vcc
	global_store_short v[24:25], v26, off offset:1024
	s_waitcnt vmcnt(62)
	v_lshlrev_b32_e32 v26, 16, v23
	v_mul_f32_e32 v26, 0x3fb8aa3b, v26
	v_and_b32_e32 v22, 0xffff0000, v22
	v_exp_f32_e32 v26, v26
	v_fmac_f32_e32 v22, v28, v27
	v_cvt_pk_bf16_f32 v27, v22, s0
	global_store_short v[24:25], v27, off offset:3584
	v_and_b32_e32 v24, 0xffff0000, v23
	v_fmac_f32_e32 v24, v26, v22
	s_waitcnt vmcnt(62)
	v_lshlrev_b32_e32 v22, 16, v21
	v_mul_f32_e32 v22, 0x3fb8aa3b, v22
	s_mov_b32 s15, 0x1701b000
	v_exp_f32_e32 v26, v22
	v_add_co_u32_e32 v22, vcc, s15, v2
	v_cvt_pk_bf16_f32 v25, v24, s0
	s_nop 0
	v_addc_co_u32_e32 v23, vcc, 0, v3, vcc
	global_store_short v[22:23], v25, off offset:2048
	s_waitcnt vmcnt(62)
	v_lshlrev_b32_e32 v22, 16, v20
	v_mul_f32_e32 v22, 0x3fb8aa3b, v22
	v_exp_f32_e32 v25, v22
	v_and_b32_e32 v21, 0xffff0000, v21
	v_fmac_f32_e32 v21, v26, v24
	v_and_b32_e32 v20, 0xffff0000, v20
	v_cvt_pk_bf16_f32 v24, v21, s0
	v_fmac_f32_e32 v20, v25, v21
	s_waitcnt vmcnt(61)
	v_lshlrev_b32_e32 v21, 16, v17
	v_mul_f32_e32 v21, 0x3fb8aa3b, v21
	v_exp_f32_e32 v21, v21
	s_mov_b32 s15, 0x1701c000
	v_add_co_u32_e32 v22, vcc, s15, v2
	v_and_b32_e32 v17, 0xffff0000, v17
	s_nop 0
	v_addc_co_u32_e32 v23, vcc, 0, v3, vcc
	global_store_short v[22:23], v24, off offset:512
	v_cvt_pk_bf16_f32 v24, v20, s0
	v_fmac_f32_e32 v17, v21, v20
	s_waitcnt vmcnt(61)
	v_lshlrev_b32_e32 v20, 16, v19
	v_mul_f32_e32 v20, 0x3fb8aa3b, v20
	s_mov_b32 s15, 0x1701d000
	global_store_short v[22:23], v24, off offset:3072
	v_exp_f32_e32 v23, v20
	v_add_co_u32_e32 v20, vcc, s15, v2
	v_cvt_pk_bf16_f32 v22, v17, s0
	s_nop 0
	v_addc_co_u32_e32 v21, vcc, 0, v3, vcc
	global_store_short v[20:21], v22, off offset:1536
	s_waitcnt vmcnt(62)
	v_lshlrev_b32_e32 v20, 16, v16
	v_and_b32_e32 v19, 0xffff0000, v19
	v_mul_f32_e32 v20, 0x3fb8aa3b, v20
	s_mov_b32 s15, 0x1701e000
	v_fmac_f32_e32 v19, v23, v17
	v_exp_f32_e32 v22, v20
	v_add_co_u32_e32 v20, vcc, s15, v2
	v_cvt_pk_bf16_f32 v17, v19, s0
	s_nop 0
	v_addc_co_u32_e32 v21, vcc, 0, v3, vcc
	global_store_short v[20:21], v17, off
	s_waitcnt vmcnt(62)
	v_lshlrev_b32_e32 v17, 16, v14
	v_mul_f32_e32 v17, 0x3fb8aa3b, v17
	v_exp_f32_e32 v17, v17
	v_and_b32_e32 v16, 0xffff0000, v16
	v_fmac_f32_e32 v16, v22, v19
	v_and_b32_e32 v14, 0xffff0000, v14
	v_cvt_pk_bf16_f32 v19, v16, s0
	v_fmac_f32_e32 v14, v17, v16
	s_waitcnt vmcnt(61)
	v_lshlrev_b32_e32 v16, 16, v12
	v_mul_f32_e32 v16, 0x3fb8aa3b, v16
	global_store_short v[20:21], v19, off offset:2560
	v_exp_f32_e32 v20, v16
	v_and_b32_e32 v12, 0xffff0000, v12
	v_cvt_pk_bf16_f32 v19, v14, s0
	s_mov_b32 s15, 0x1701f000
	v_fmac_f32_e32 v12, v20, v14
	s_waitcnt vmcnt(61)
	v_lshlrev_b32_e32 v14, 16, v18
	v_mul_f32_e32 v14, 0x3fb8aa3b, v14
	v_exp_f32_e32 v14, v14
	v_and_b32_e32 v18, 0xffff0000, v18
	v_add_co_u32_e32 v16, vcc, s15, v2
	v_fmac_f32_e32 v18, v14, v12
	s_waitcnt vmcnt(60)
	v_lshlrev_b32_e32 v14, 16, v15
	v_addc_co_u32_e32 v17, vcc, 0, v3, vcc
	v_mul_f32_e32 v14, 0x3fb8aa3b, v14
	global_store_short v[16:17], v19, off offset:1024
	v_cvt_pk_bf16_f32 v19, v12, s0
	v_exp_f32_e32 v14, v14
	s_mov_b32 s15, 0x17020000
	global_store_short v[16:17], v19, off offset:3584
	v_add_co_u32_e32 v16, vcc, s15, v2
	v_cvt_pk_bf16_f32 v12, v18, s0
	s_nop 0
	v_addc_co_u32_e32 v17, vcc, 0, v3, vcc
	global_store_short v[16:17], v12, off offset:2048
	v_and_b32_e32 v12, 0xffff0000, v15
	v_fmac_f32_e32 v12, v14, v18
	s_waitcnt vmcnt(62)
	v_lshlrev_b32_e32 v14, 16, v13
	v_mul_f32_e32 v14, 0x3fb8aa3b, v14
	v_exp_f32_e32 v17, v14
	v_and_b32_e32 v13, 0xffff0000, v13
	v_cvt_pk_bf16_f32 v16, v12, s0
	s_mov_b32 s15, 0x17021000
	v_fmac_f32_e32 v13, v17, v12
	s_waitcnt vmcnt(61)
	v_lshlrev_b32_e32 v12, 16, v10
	v_mul_f32_e32 v12, 0x3fb8aa3b, v12
	v_exp_f32_e32 v12, v12
	v_add_co_u32_e32 v14, vcc, s15, v2
	v_and_b32_e32 v10, 0xffff0000, v10
	s_nop 0
	v_addc_co_u32_e32 v15, vcc, 0, v3, vcc
	v_fmac_f32_e32 v10, v12, v13
	s_waitcnt vmcnt(60)
	v_lshlrev_b32_e32 v12, 16, v11
	global_store_short v[14:15], v16, off offset:512
	v_cvt_pk_bf16_f32 v16, v13, s0
	v_mul_f32_e32 v12, 0x3fb8aa3b, v12
	global_store_short v[14:15], v16, off offset:3072
	v_exp_f32_e32 v15, v12
	s_mov_b32 s15, 0x17022000
	v_add_co_u32_e32 v12, vcc, s15, v2
	v_cvt_pk_bf16_f32 v14, v10, s0
	s_nop 0
	v_addc_co_u32_e32 v13, vcc, 0, v3, vcc
	global_store_short v[12:13], v14, off offset:1536
	v_and_b32_e32 v12, 0xffff0000, v11
	v_fmac_f32_e32 v12, v15, v10
	s_waitcnt vmcnt(62)
	v_lshlrev_b32_e32 v10, 16, v7
	v_mul_f32_e32 v10, 0x3fb8aa3b, v10
	v_exp_f32_e32 v14, v10
	v_and_b32_e32 v7, 0xffff0000, v7
	v_cvt_pk_bf16_f32 v13, v12, s0
	s_mov_b32 s15, 0x17023000
	v_fmac_f32_e32 v7, v14, v12
	s_waitcnt vmcnt(61)
	v_lshlrev_b32_e32 v12, 16, v6
	v_add_co_u32_e32 v10, vcc, s15, v2
	v_mul_f32_e32 v12, 0x3fb8aa3b, v12
	s_nop 0
	v_addc_co_u32_e32 v11, vcc, 0, v3, vcc
	v_exp_f32_e32 v12, v12
	global_store_short v[10:11], v13, off
	v_cvt_pk_bf16_f32 v13, v7, s0
	global_store_short v[10:11], v13, off offset:2560
	v_and_b32_e32 v10, 0xffff0000, v6
	s_waitcnt vmcnt(62)
	v_lshlrev_b32_e32 v6, 16, v0
	v_mul_f32_e32 v6, 0x3fb8aa3b, v6
	v_fmac_f32_e32 v10, v12, v7
	v_exp_f32_e32 v12, v6
	v_and_b32_e32 v0, 0xffff0000, v0
	v_cvt_pk_bf16_f32 v11, v10, s0
	s_mov_b32 s15, 0x17024000
	v_fmac_f32_e32 v0, v12, v10
	s_waitcnt vmcnt(61)
	v_lshlrev_b32_e32 v10, 16, v4
	v_add_co_u32_e32 v6, vcc, s15, v2
	v_mul_f32_e32 v10, 0x3fb8aa3b, v10
	s_nop 0
	v_addc_co_u32_e32 v7, vcc, 0, v3, vcc
	v_exp_f32_e32 v10, v10
	global_store_short v[6:7], v11, off offset:1024
	v_cvt_pk_bf16_f32 v11, v0, s0
	global_store_short v[6:7], v11, off offset:3584
	s_waitcnt vmcnt(62)
	v_lshlrev_b32_e32 v6, 16, v8
	v_and_b32_e32 v4, 0xffff0000, v4
	v_mul_f32_e32 v6, 0x3fb8aa3b, v6
	s_mov_b32 s15, 0x17025000
	v_fmac_f32_e32 v4, v10, v0
	v_exp_f32_e32 v10, v6
	v_add_co_u32_e32 v6, vcc, s15, v2
	v_cvt_pk_bf16_f32 v0, v4, s0
	s_nop 0
	v_addc_co_u32_e32 v7, vcc, 0, v3, vcc
	global_store_short v[6:7], v0, off offset:2048
	s_waitcnt vmcnt(62)
	v_lshlrev_b32_e32 v6, 16, v9
	v_mul_f32_e32 v6, 0x3fb8aa3b, v6
	v_and_b32_e32 v0, 0xffff0000, v8
	v_exp_f32_e32 v8, v6
	s_mov_b32 s15, 0x17026000
	v_fmac_f32_e32 v0, v10, v4
	v_add_co_u32_e32 v6, vcc, s15, v2
	v_cvt_pk_bf16_f32 v4, v0, s0
	s_nop 0
	v_addc_co_u32_e32 v7, vcc, 0, v3, vcc
	global_store_short v[6:7], v4, off offset:512
	v_and_b32_e32 v4, 0xffff0000, v9
	v_fmac_f32_e32 v4, v8, v0
	s_waitcnt vmcnt(62)
	v_lshlrev_b32_e32 v0, 16, v5
	s_add_i32 s14, s14, s92
	v_readlane_b32 s12, v253, 43
	v_mul_f32_e32 v0, 0x3fb8aa3b, v0
	s_mov_b32 s15, 0x17027000
	v_readlane_b32 s13, v253, 44
	s_add_u32 s34, s34, s12
	v_exp_f32_e32 v0, v0
	v_add_co_u32_e32 v2, vcc, s15, v2
	s_addc_u32 s35, s35, s13
	s_mul_i32 s15, s92, 0x28000
	s_add_u32 s22, s22, s15
	s_mul_hi_i32 s15, s92, 0x28000
	s_addc_u32 s23, s23, s15
	v_readlane_b32 s12, v253, 55
	v_and_b32_e32 v5, 0xffff0000, v5
	v_readlane_b32 s13, v253, 56
	s_add_u32 s2, s2, s12
	v_fmac_f32_e32 v5, v0, v4
	s_addc_u32 s3, s3, s13
	v_cvt_pk_bf16_f32 v8, v4, s0
	v_cvt_pk_bf16_f32 v0, v5, s0
	v_addc_co_u32_e32 v3, vcc, 0, v3, vcc
	s_cmpk_gt_i32 s14, 0xff
	global_store_short v[6:7], v8, off offset:3072
	global_store_short v[2:3], v0, off offset:1536
	s_cbranch_scc0 .LBB0_290
	v_readlane_b32 s15, v255, 30
	s_cmp_eq_u32 s15, 2
	s_cbranch_scc1 .Lm3_merge
.Lm3_hgrn_setup:
	s_add_u32 s70, s8, 0x39400000
	s_addc_u32 s71, s9, 0
	s_add_u32 s72, s8, 0x17000400
	s_addc_u32 s73, s9, 0
	v_readlane_b32 s74, v253, 51
	v_readlane_b32 s2, v254, 3
	v_readlane_b32 s3, v254, 4
	s_branch .LBB0_293

.LBB0_357:
	v_readlane_b32 s15, v255, 30
	s_cmp_eq_u32 s15, 1
	s_cbranch_scc0 .Lm3_merge
	s_mov_b32 s15, 2
	v_writelane_b32 v255, s15, 30
	v_readlane_b32 s2, v253, 47
	v_readlane_b32 s22, v253, 45
	v_readlane_b32 s34, v253, 41
	v_readlane_b32 s12, v254, 3
	v_readlane_b32 s3, v253, 48
	v_readlane_b32 s23, v253, 46
	v_readlane_b32 s35, v253, 42
	s_mov_b32 s14, s12
	v_readlane_b32 s13, v254, 4
	s_branch .LBB0_290
